# alpha phase: bf16 packing by v_cvt_pk_bf16_f32 instead of the integer RNE bit trick
# baseline (speedup 1.0000x reference)
; __device__ __forceinline__ float bf_lo(unsigned w) { return __uint_as_float(w << 16); }
; __device__ __forceinline__ float bf_hi(unsigned w) { return __uint_as_float(w & 0xffff0000u); }
; __device__ __forceinline__ unsigned pk2(float lo, float hi) { return f2bf(lo) | (f2bf(hi) << 16); }
; __device__ __forceinline__ void alpha_phase(const Ctx& C) {
;     ...
;     for (int tg = gw; tg < M / 4; tg += NGW) {
; #pragma unroll
;         for (int i = 0; i < 3; ++i) { const int L = C.lane + 64 * i; const size_t tok = (size_t)4 * tg + L / 48; const int ch = L % 48, h = ch >> 3, jj = h & 1, g = h >> 1;
;             const float l0 = LSE[tok * 6 + jj], l1 = LSE[tok * 6 + 2 + jj], l2 = LSE[tok * 6 + 4 + jj];
;             const float mx = fmaxf(l0, fmaxf(l1, l2)); const float e0 = __expf(l0 - mx), e1 = __expf(l1 - mx), e2 = __expf(l2 - mx);
;             const float al = (g == 0 ? e0 : (g == 1 ? e1 : e2)) / (e0 + e1 + e2);
;             const u32x4 v = *(const u32x4*)(AO + tok * AW + ch * 8); u32x4 o;
;             o.x = pk2(bf_lo(v.x) * al, bf_hi(v.x) * al); o.y = pk2(bf_lo(v.y) * al, bf_hi(v.y) * al); o.z = pk2(bf_lo(v.z) * al, bf_hi(v.z) * al); o.w = pk2(bf_lo(v.w) * al, bf_hi(v.w) * al);
;             *(u32x4*)(MIX + tok * DM + ch * 8) = o; }
.LBB0_359:
	v_lshl_add_u64 v[60:61], v[12:13], 0, s[28:29]
	global_load_dword v72, v[60:61], off offset:-8
	global_load_dword v62, v[60:61], off
	global_load_dword v60, v[60:61], off offset:8
	s_add_i32 s2, s2, s10
	v_lshl_add_u64 v[12:13], v[12:13], 0, s[34:35]
	s_cmpk_lt_i32 s2, 0x4000
	v_lshl_add_u64 v[76:77], v[14:15], 0, s[28:29]
	global_load_dword v88, v[76:77], off offset:-8
	global_load_dword v78, v[76:77], off
	global_load_dword v76, v[76:77], off offset:8
	v_lshl_add_u64 v[14:15], v[14:15], 0, s[34:35]
	v_lshl_add_u64 v[92:93], v[4:5], 0, s[28:29]
	global_load_dword v104, v[92:93], off offset:-8
	global_load_dword v94, v[92:93], off
	global_load_dword v92, v[92:93], off offset:8
	v_lshl_add_u64 v[4:5], v[4:5], 0, s[34:35]
	s_waitcnt vmcnt(0)
	v_max3_f32 v61, v72, v62, v60
	v_sub_f32_e32 v62, v62, v61
	v_sub_f32_e32 v60, v60, v61
	v_sub_f32_e32 v72, v72, v61
	v_mul_f32_e32 v62, 0x3fb8aa3b, v62
	v_mul_f32_e32 v60, 0x3fb8aa3b, v60
	v_mul_f32_e32 v72, 0x3fb8aa3b, v72
	v_exp_f32_e32 v62, v62
	v_exp_f32_e32 v60, v60
	v_exp_f32_e32 v72, v72
	v_cndmask_b32_e64 v61, v60, v62, s[38:39]
	v_cndmask_b32_e64 v61, v61, v72, s[36:37]
	v_add_f32_e32 v72, v72, v62
	v_add_f32_e32 v72, v60, v72
	v_div_scale_f32 v60, s[4:5], v72, v72, v61
	v_rcp_f32_e32 v62, v60
	s_nop 0
	v_fma_f32 v63, -v60, v62, 1.0
	v_fmac_f32_e32 v62, v63, v62
	v_div_scale_f32 v63, vcc, v61, v72, v61
	v_mul_f32_e32 v64, v63, v62
	v_fma_f32 v65, -v60, v64, v63
	v_fmac_f32_e32 v64, v65, v62
	v_fma_f32 v60, -v60, v64, v63
	v_div_fmas_f32 v60, v60, v62, v64
	v_div_fixup_f32 v64, v60, v72, v61
	v_max3_f32 v77, v88, v78, v76
	v_sub_f32_e32 v78, v78, v77
	v_sub_f32_e32 v76, v76, v77
	v_sub_f32_e32 v88, v88, v77
	v_mul_f32_e32 v78, 0x3fb8aa3b, v78
	v_mul_f32_e32 v76, 0x3fb8aa3b, v76
	v_mul_f32_e32 v88, 0x3fb8aa3b, v88
	v_exp_f32_e32 v78, v78
	v_exp_f32_e32 v76, v76
	v_exp_f32_e32 v88, v88
	v_cndmask_b32_e64 v77, v76, v78, s[42:43]
	v_cndmask_b32_e64 v77, v77, v88, s[40:41]
	v_add_f32_e32 v88, v88, v78
	v_add_f32_e32 v88, v76, v88
	v_div_scale_f32 v76, s[4:5], v88, v88, v77
	v_rcp_f32_e32 v78, v76
	s_nop 0
	v_fma_f32 v79, -v76, v78, 1.0
	v_fmac_f32_e32 v78, v79, v78
	v_div_scale_f32 v79, vcc, v77, v88, v77
	v_mul_f32_e32 v80, v79, v78
	v_fma_f32 v81, -v76, v80, v79
	v_fmac_f32_e32 v80, v81, v78
	v_fma_f32 v76, -v76, v80, v79
	v_div_fmas_f32 v76, v76, v78, v80
	v_div_fixup_f32 v80, v76, v88, v77
	v_max3_f32 v93, v104, v94, v92
	v_sub_f32_e32 v94, v94, v93
	v_sub_f32_e32 v92, v92, v93
	v_sub_f32_e32 v104, v104, v93
	v_mul_f32_e32 v94, 0x3fb8aa3b, v94
	v_mul_f32_e32 v92, 0x3fb8aa3b, v92
	v_mul_f32_e32 v104, 0x3fb8aa3b, v104
	v_exp_f32_e32 v94, v94
	v_exp_f32_e32 v92, v92
	v_exp_f32_e32 v104, v104
	v_cndmask_b32_e64 v93, v92, v94, s[46:47]
	v_cndmask_b32_e64 v93, v93, v104, s[44:45]
	v_add_f32_e32 v104, v104, v94
	v_add_f32_e32 v104, v92, v104
	v_div_scale_f32 v92, s[4:5], v104, v104, v93
	v_rcp_f32_e32 v94, v92
	s_nop 0
	v_fma_f32 v95, -v92, v94, 1.0
	v_fmac_f32_e32 v94, v95, v94
	v_div_scale_f32 v95, vcc, v93, v104, v93
	v_mul_f32_e32 v96, v95, v94
	v_fma_f32 v97, -v92, v96, v95
	v_fmac_f32_e32 v96, v97, v94
	v_fma_f32 v92, -v92, v96, v95
	v_div_fmas_f32 v92, v92, v94, v96
	v_lshl_add_u64 v[60:61], v[6:7], 0, s[28:29]
	global_load_dwordx4 v[60:63], v[60:61], off
	v_lshl_add_u64 v[6:7], v[6:7], 0, s[30:31]
	v_lshl_add_u64 v[76:77], v[18:19], 0, s[28:29]
	global_load_dwordx4 v[76:79], v[76:77], off
	v_lshl_add_u64 v[18:19], v[18:19], 0, s[30:31]
	v_lshl_add_u64 v[94:95], v[8:9], 0, s[28:29]
	global_load_dwordx4 v[94:97], v[94:95], off
	v_div_fixup_f32 v92, v92, v104, v93
	v_lshl_add_u64 v[8:9], v[8:9], 0, s[30:31]
	s_waitcnt vmcnt(0)
	v_lshlrev_b32_e32 v67, 16, v61
	v_lshlrev_b32_e32 v66, 16, v60
	v_and_b32_e32 v61, 0xffff0000, v61
	v_and_b32_e32 v60, 0xffff0000, v60
	v_lshlrev_b32_e32 v69, 16, v63
	v_lshlrev_b32_e32 v68, 16, v62
	v_and_b32_e32 v63, 0xffff0000, v63
	v_and_b32_e32 v62, 0xffff0000, v62
	v_pk_mul_f32 v[60:61], v[64:65], v[60:61] op_sel_hi:[0,1]
	v_pk_mul_f32 v[62:63], v[64:65], v[62:63] op_sel_hi:[0,1]
	v_pk_mul_f32 v[66:67], v[64:65], v[66:67] op_sel_hi:[0,1]
	v_pk_mul_f32 v[68:69], v[64:65], v[68:69] op_sel_hi:[0,1]
	v_cvt_pk_bf16_f32 v63, v69, v63
	v_cvt_pk_bf16_f32 v62, v68, v62
	v_cvt_pk_bf16_f32 v61, v67, v61
	v_cvt_pk_bf16_f32 v60, v66, v60
	v_lshl_add_u64 v[64:65], v[2:3], 0, s[28:29]
	global_store_dwordx4 v[64:65], v[60:63], off
	v_lshl_add_u64 v[2:3], v[2:3], 0, s[24:25]
	s_nop 0
	v_lshlrev_b32_e32 v83, 16, v77
	v_lshlrev_b32_e32 v82, 16, v76
	v_and_b32_e32 v77, 0xffff0000, v77
	v_and_b32_e32 v76, 0xffff0000, v76
	v_lshlrev_b32_e32 v85, 16, v79
	v_lshlrev_b32_e32 v84, 16, v78
	v_and_b32_e32 v79, 0xffff0000, v79
	v_and_b32_e32 v78, 0xffff0000, v78
	v_pk_mul_f32 v[76:77], v[80:81], v[76:77] op_sel_hi:[0,1]
	v_pk_mul_f32 v[78:79], v[80:81], v[78:79] op_sel_hi:[0,1]
	v_pk_mul_f32 v[82:83], v[80:81], v[82:83] op_sel_hi:[0,1]
	v_pk_mul_f32 v[84:85], v[80:81], v[84:85] op_sel_hi:[0,1]
	v_cvt_pk_bf16_f32 v79, v85, v79
	v_cvt_pk_bf16_f32 v78, v84, v78
	v_cvt_pk_bf16_f32 v77, v83, v77
	v_cvt_pk_bf16_f32 v76, v82, v76
	v_lshl_add_u64 v[80:81], v[16:17], 0, s[28:29]
	global_store_dwordx4 v[80:81], v[76:79], off
	v_lshl_add_u64 v[16:17], v[16:17], 0, s[24:25]
	s_nop 0
	v_lshlrev_b32_e32 v99, 16, v95
	v_lshlrev_b32_e32 v98, 16, v94
	v_and_b32_e32 v95, 0xffff0000, v95
	v_and_b32_e32 v94, 0xffff0000, v94
	v_lshlrev_b32_e32 v101, 16, v97
	v_lshlrev_b32_e32 v100, 16, v96
	v_and_b32_e32 v97, 0xffff0000, v97
	v_and_b32_e32 v96, 0xffff0000, v96
	v_pk_mul_f32 v[98:99], v[92:93], v[98:99] op_sel_hi:[0,1]
	v_pk_mul_f32 v[94:95], v[92:93], v[94:95] op_sel_hi:[0,1]
	v_pk_mul_f32 v[100:101], v[92:93], v[100:101] op_sel_hi:[0,1]
	v_pk_mul_f32 v[92:93], v[92:93], v[96:97] op_sel_hi:[0,1]
	v_cvt_pk_bf16_f32 v108, v101, v93
	v_cvt_pk_bf16_f32 v93, v99, v95
	v_cvt_pk_bf16_f32 v109, v100, v92
	v_cvt_pk_bf16_f32 v92, v98, v94
	v_mov_b32_e32 v95, v108
	v_mov_b32_e32 v94, v109
	v_lshl_add_u64 v[96:97], v[10:11], 0, s[28:29]
	v_lshl_add_u64 v[10:11], v[10:11], 0, s[24:25]
	global_store_dwordx4 v[96:97], v[92:95], off
	s_cbranch_scc1 .LBB0_359
	v_readlane_b32 s6, v255, 49
	v_readlane_b32 s46, v255, 51
	v_readlane_b32 s48, v253, 47
	v_readlane_b32 s7, v255, 50
	v_readlane_b32 s47, v255, 52
	v_readlane_b32 s49, v253, 48
